# prompt attention: butterfly reductions as DPP / permlane-swap register ops instead of ds_bpermute LDS round trips
# speedup vs baseline: 1.0058x; 1.0030x over previous
; __device__ __forceinline__ void attn_item(const Args& a, LAS unsigned char* lds, int layer, bool is_sample, int b, int c, int kvh, int seq_row0, int nchunks, bf16_t* proj, const int tid) {
;     const int wave = __builtin_amdgcn_readfirstlane(tid >> 6), lane = tid & 63, fr = lane & 15, fq = lane >> 4;
;     const int row0 = seq_row0 + c * 64;
;     const float* kng = a.in[21] + layer * 64;
;     u32x4 qraw[2][2];
;     {
;         const int hq_ = kvh * 4 + (wave >> 1);
; #pragma unroll
;         for (int sub = 0; sub < 2; ++sub) { const bf16_t* qp_ = proj + (size_t)(row0 + (wave & 1) * 32 + sub * 16 + fr) * PN + C_Q + hq_ * 64;
; #pragma unroll
;             for (int ks = 0; ks < 2; ++ks) qraw[sub][ks] = *(const u32x4*)(qp_ + 32 * ks + 8 * fq); }
;     }
; #pragma unroll
;     for (int i = 0; i < 3; ++i) {
;         const int slot = tid + 512 * i, kl = slot >> 3, oc = slot & 7;
;         const int pos = c * 64 - 128 + kl;
;         float kf[8], vf[8];
;         if (is_sample && kl < 128) {
;             const size_t off = (((size_t)(layer * NSB + b) * 128 + kl) * NKVH + kvh) * 64 + oc * 8;
;             const f32x4 k0 = *(const f32x4*)(a.in[2] + off), k1 = *(const f32x4*)(a.in[2] + off + 4), v0 = *(const f32x4*)(a.in[3] + off), v1 = *(const f32x4*)(a.in[3] + off + 4);
; #pragma unroll
;             for (int e = 0; e < 4; ++e) { kf[e] = k0[e]; kf[4 + e] = k1[e]; vf[e] = v0[e]; vf[4 + e] = v1[e]; }
;         } else if (pos >= 0) {
;             const bf16_t* rp = proj + (size_t)(seq_row0 + pos) * PN;
;             const u32x4 kw = *(const u32x4*)(rp + C_K + kvh * 64 + oc * 8), vw = *(const u32x4*)(rp + C_V + kvh * 64 + oc * 8);
.LBB0_454:
	s_and_b64 vcc, exec, s[4:5]
	s_cbranch_vccz .LBB0_482
	s_ashr_i32 s4, s16, 7
	v_readlane_b32 s5, v255, 38
	s_add_i32 s6, s4, s5
	v_mov_b32_e32 v36, v166
	s_lshl_b32 s4, s6, 11
	v_readlane_b32 s5, v255, 31
	s_and_b32 s7, s3, 3
	s_bfe_u32 s21, s3, 0x50002
	s_sub_i32 s43, s4, s5
	v_readfirstlane_b32 s4, v36
	v_and_b32_e32 v41, 15, v36
	s_lshl_b32 s38, s21, 6
	s_lshl_b32 s40, s7, 2
	s_ashr_i32 s20, s4, 7
	s_lshr_b32 s4, s4, 1
	s_or_b32 s23, s43, s38
	s_add_i32 s39, s20, s40
	v_and_or_b32 v92, s4, 32, v41
	v_or_b32_e32 v12, s23, v92
	s_lshl_b32 s8, s39, 6
	v_mov_b64_e32 v[10:11], s[18:19]
	s_ashr_i32 s9, s8, 31
	v_mad_i64_i32 v[2:3], s[4:5], v12, s33, v[10:11]
	v_bfe_u32 v42, v36, 4, 2
	s_lshl_b64 s[4:5], s[8:9], 1
	v_lshl_add_u64 v[2:3], v[2:3], 0, s[4:5]
	v_lshlrev_b32_e32 v0, 4, v42
	v_or_b32_e32 v12, 16, v12
	v_lshl_add_u64 v[2:3], v[2:3], 0, v[0:1]
	s_mov_b64 s[16:17], 0x2800
	s_movk_i32 s10, 0x2000
	v_mad_i64_i32 v[10:11], s[14:15], v12, s33, v[10:11]
	v_lshl_add_u64 v[6:7], v[2:3], 0, s[16:17]
	v_add_co_u32_e32 v2, vcc, s10, v2
	v_lshl_add_u64 v[10:11], v[10:11], 0, s[4:5]
	s_nop 0
	v_addc_co_u32_e32 v3, vcc, 0, v3, vcc
	v_lshl_add_u64 v[10:11], v[10:11], 0, v[0:1]
	v_lshl_add_u64 v[14:15], v[10:11], 0, s[16:17]
	v_add_co_u32_e32 v10, vcc, s10, v10
	global_load_dwordx4 v[2:5], v[2:3], off offset:2048
	s_nop 0
	global_load_dwordx4 v[6:9], v[6:7], off offset:64
	v_addc_co_u32_e32 v11, vcc, 0, v11, vcc
	global_load_dwordx4 v[10:13], v[10:11], off offset:2048
	s_nop 0
	global_load_dwordx4 v[14:17], v[14:15], off offset:64
	v_and_b32_e32 v19, 7, v36
	s_add_i32 s44, s38, 0xffffff80
	s_lshl_b32 s41, s7, 6
	v_readlane_b32 s4, v255, 14
	v_ashrrev_i32_e32 v37, 3, v36
	v_lshlrev_b32_e32 v43, 3, v19
	v_lshlrev_b32_e32 v0, 5, v19
	v_readlane_b32 s5, v255, 15
	s_cmp_lt_u32 s21, 30
	v_add_u32_e32 v40, s44, v37
	s_mov_b64 s[28:29], 0x2800
	s_movk_i32 s36, 0x2000
	v_lshl_add_u64 v[38:39], s[4:5], 0, v[0:1]
	s_cselect_b64 s[14:15], -1, 0
	s_or_b32 s42, s38, 0xfffff800
	s_ashr_i32 s7, s6, 31
	v_cmp_lt_i32_e32 vcc, -1, v40
	v_mov_b32_e32 v18, 0
	v_lshlrev_b32_e32 v0, 1, v43
	v_mov_b32_e32 v20, 0
	v_mov_b32_e32 v21, 0
	v_mov_b32_e32 v22, 0
	v_mov_b32_e32 v23, 0
	v_mov_b32_e32 v24, 0
	v_mov_b32_e32 v25, 0
	v_mov_b32_e32 v26, 0
	v_mov_b32_e32 v27, 0
	v_mov_b32_e32 v28, 0
	v_mov_b32_e32 v29, 0
	v_mov_b32_e32 v30, 0
	v_mov_b32_e32 v31, 0
	v_mov_b32_e32 v32, 0
	v_mov_b32_e32 v33, 0
	v_mov_b32_e32 v34, 0
	v_mov_b32_e32 v35, 0
	v_add_u32_e32 v244, s43, v40
	v_mov_b64_e32 v[240:241], s[18:19]
	v_mad_i64_i32 v[240:241], s[4:5], v244, s33, v[240:241]
	s_lshl_b32 s100, s41, 1
	s_mov_b32 s101, 0
	v_lshl_add_u64 v[240:241], v[240:241], 0, s[100:101]
	v_lshl_add_u64 v[240:241], v[240:241], 0, v[0:1]
	s_mov_b64 s[100:101], 0x11b000
	v_lshl_add_u64 v[242:243], v[240:241], 0, s[100:101]
	global_load_dwordx4 v[232:235], v[38:39], off
	global_load_dwordx4 v[236:239], v[38:39], off offset:16
	global_load_dwordx4 v[216:219], v[242:243], off
	global_load_dwordx4 v[220:223], v[242:243], off offset:512
	s_mov_b64 s[100:101], 0x233000
	v_lshl_add_u64 v[242:243], v[240:241], 0, s[100:101]
	global_load_dwordx4 v[224:227], v[242:243], off
	global_load_dwordx4 v[228:231], v[242:243], off offset:512
	s_and_saveexec_b64 s[16:17], vcc
	s_cbranch_execz .LBB0_459
; __device__ __forceinline__ float bflo(unsigned w) { return __uint_as_float(w << 16); }
; __device__ __forceinline__ float bfhi(unsigned w) { return __uint_as_float(w & 0xffff0000u); }
; __device__ __forceinline__ void attn_item(const Args& a, LAS unsigned char* lds, int layer, bool is_sample, int b, int c, int kvh, int seq_row0, int nchunks, bf16_t* proj, const int tid) {
;     ...
;         } else if (pos >= 0) {
;             const bf16_t* rp = proj + (size_t)(seq_row0 + pos) * PN;
;             const u32x4 kw = *(const u32x4*)(rp + C_K + kvh * 64 + oc * 8), vw = *(const u32x4*)(rp + C_V + kvh * 64 + oc * 8);
;             kf[0] = bflo(kw.x); kf[1] = bfhi(kw.x); kf[2] = bflo(kw.y); kf[3] = bfhi(kw.y); kf[4] = bflo(kw.z); kf[5] = bfhi(kw.z); kf[6] = bflo(kw.w); kf[7] = bfhi(kw.w);
;             vf[0] = bflo(vw.x); vf[1] = bfhi(vw.x); vf[2] = bflo(vw.y); vf[3] = bfhi(vw.y); vf[4] = bflo(vw.z); vf[5] = bfhi(vw.z); vf[6] = bflo(vw.w); vf[7] = bfhi(vw.w);
;             float ss = 0.f;
; #pragma unroll
;             for (int e = 0; e < 8; ++e) ss += kf[e] * kf[e];
;             ss += __shfl_xor(ss, 1); ss += __shfl_xor(ss, 2); ss += __shfl_xor(ss, 4);
;             const float rs = rsqrtf(ss * (1.f / 64.f) + EPS);
;             const f32x4 g0 = *(const f32x4*)(kng + oc * 8), g1 = *(const f32x4*)(kng + oc * 8 + 4);
; #pragma unroll
;             for (int e = 0; e < 4; ++e) { kf[e] = kf[e] * rs * g0[e]; kf[4 + e] = kf[4 + e] * rs * g1[e]; }
;             if (kl >= 128 && (is_sample || c >= nchunks - 2)) {
;                 const int orow = is_sample ? (kl - 128) : (c - (nchunks - 2)) * 64 + (kl - 128);
;                 const size_t nb_ = is_sample ? NSB : NPB; const int lr = is_sample ? DSEQ : 128;
;                 const size_t off = (((size_t)(layer * nb_ + b) * lr + orow) * NKVH + kvh) * 64 + oc * 8;
;                 float* ko = a.out + (is_sample ? O_KS : O_KP) + off; float* vo = a.out + (is_sample ? O_VS : O_VP) + off;
;                 *(f32x4*)ko = (f32x4){kf[0], kf[1], kf[2], kf[3]}; *(f32x4*)(ko + 4) = (f32x4){kf[4], kf[5], kf[6], kf[7]};
;                 *(f32x4*)vo = (f32x4){vf[0], vf[1], vf[2], vf[3]}; *(f32x4*)(vo + 4) = (f32x4){vf[4], vf[5], vf[6], vf[7]};
	v_add_u32_e32 v22, s43, v40
	v_mov_b64_e32 v[20:21], s[18:19]
	v_mad_i64_i32 v[20:21], s[4:5], v22, s33, v[20:21]
	s_lshl_b32 s10, s41, 1
	v_lshl_add_u64 v[20:21], v[20:21], 0, s[10:11]
	v_lshl_add_u64 v[20:21], v[20:21], 0, v[0:1]
	v_add_co_u32_e32 v24, vcc, 0x3000, v20
	s_movk_i32 s4, 0x7f
	s_nop 0
	v_addc_co_u32_e32 v25, vcc, 0, v21, vcc
	global_load_dwordx4 v[20:23], v[24:25], off
	s_nop 0
	global_load_dwordx4 v[24:27], v[24:25], off offset:512
	s_nop 0
	v_cmp_lt_i32_e32 vcc, v204, v203
	s_xor_b64 s[46:47], s[14:15], -1
	s_waitcnt vmcnt(1)
	v_mov_b32_e32 v28, v232
	v_mov_b32_e32 v29, v233
	v_mov_b32_e32 v30, v234
	v_mov_b32_e32 v31, v235
	v_mov_b32_e32 v32, v236
	v_mov_b32_e32 v33, v237
	v_mov_b32_e32 v34, v238
	v_mov_b32_e32 v35, v239
	v_lshlrev_b32_e32 v48, 16, v20
	v_and_b32_e32 v49, 0xffff0000, v20
	v_lshlrev_b32_e32 v50, 16, v21
	v_and_b32_e32 v51, 0xffff0000, v21
	v_pk_mul_f32 v[52:53], v[48:49], v[48:49]
	v_pk_mul_f32 v[54:55], v[50:51], v[50:51]
	v_add_f32_e32 v52, v52, v53
	v_lshlrev_b32_e32 v46, 16, v22
	v_and_b32_e32 v47, 0xffff0000, v22
	v_add_f32_e32 v52, v54, v52
	v_and_b32_e32 v44, 0xffff0000, v23
	v_lshlrev_b32_e32 v45, 16, v23
	v_pk_mul_f32 v[22:23], v[46:47], v[46:47]
	v_add_f32_e32 v52, v55, v52
	v_add_f32_e32 v22, v22, v52
	v_pk_mul_f32 v[20:21], v[44:45], v[44:45]
	v_add_f32_e32 v22, v23, v22
	v_cndmask_b32_e32 v40, v201, v204, vcc
	v_add_f32_e32 v21, v21, v22
	v_lshlrev_b32_e32 v40, 2, v40
	v_add_f32_e32 v20, v20, v21
	v_cmp_lt_i32_e32 vcc, s4, v37
	v_cmp_lt_i32_e64 s[4:5], v205, v203
	s_and_b64 s[46:47], vcc, s[46:47]
	s_waitcnt lgkmcnt(0)
	s_nop 1
	v_add_f32_dpp v21, v20, v20 quad_perm:[1,0,3,2] row_mask:0xf bank_mask:0xf
	v_cndmask_b32_e64 v22, v201, v205, s[4:5]
	v_lshlrev_b32_e32 v22, 2, v22
	v_cmp_lt_i32_e64 s[4:5], v206, v203
	s_waitcnt lgkmcnt(0)
	s_nop 1
	v_add_f32_dpp v40, v21, v21 quad_perm:[2,3,0,1] row_mask:0xf bank_mask:0xf
	v_cndmask_b32_e64 v20, v201, v206, s[4:5]
	v_lshlrev_b32_e32 v23, 2, v20
	s_waitcnt vmcnt(0)
	v_lshlrev_b32_e32 v22, 16, v25
	v_and_b32_e32 v23, 0xffff0000, v25
	s_mov_b32 s4, 0x800000
	v_lshlrev_b32_e32 v20, 16, v24
	s_waitcnt lgkmcnt(0)
	s_nop 1
	v_add_f32_dpp v25, v40, v40 row_half_mirror row_mask:0xf bank_mask:0xf
	v_fmamk_f32 v25, v25, 0x3c800000, v167
	v_mul_f32_e32 v40, 0x4b800000, v25
	v_cmp_gt_f32_e64 s[4:5], s4, v25
	v_and_b32_e32 v21, 0xffff0000, v24
	v_lshlrev_b32_e32 v24, 16, v26
	v_cndmask_b32_e64 v25, v25, v40, s[4:5]
	v_rsq_f32_e32 v40, v25
	v_and_b32_e32 v25, 0xffff0000, v26
	v_lshlrev_b32_e32 v26, 16, v27
	v_and_b32_e32 v27, 0xffff0000, v27
	v_mul_f32_e32 v52, 0x45800000, v40
	v_cndmask_b32_e64 v40, v40, v52, s[4:5]
	v_pk_mul_f32 v[48:49], v[40:41], v[48:49] op_sel_hi:[0,1]
	v_pk_mul_f32 v[46:47], v[40:41], v[46:47] op_sel_hi:[0,1]
	v_pk_mul_f32 v[50:51], v[40:41], v[50:51] op_sel_hi:[0,1]
	v_pk_mul_f32 v[44:45], v[40:41], v[44:45] op_sel_hi:[0,1]
	s_waitcnt vmcnt(1)
	v_pk_mul_f32 v[28:29], v[28:29], v[48:49]
	s_waitcnt vmcnt(0)
	v_pk_mul_f32 v[32:33], v[32:33], v[46:47]
	v_pk_mul_f32 v[30:31], v[30:31], v[50:51]
	v_pk_mul_f32 v[34:35], v[34:35], v[44:45] op_sel:[0,1] op_sel_hi:[1,0]
	s_and_saveexec_b64 s[4:5], s[46:47]
	s_cbranch_execz .LBB0_458
	s_lshl_b64 s[46:47], s[6:7], 7
	v_readlane_b32 s48, v255, 16
	v_add_u32_e32 v44, s42, v37
	v_readlane_b32 s49, v255, 17
	s_add_u32 s46, s46, s48
	s_addc_u32 s47, s47, s49
	v_ashrrev_i32_e32 v45, 31, v44
	v_lshl_add_u64 v[44:45], s[46:47], 0, v[44:45]
	v_lshlrev_b64 v[44:45], 8, v[44:45]
	v_or3_b32 v45, v45, 0, 0
	v_or3_b32 v44, v44, v43, s41
	v_readlane_b32 s46, v253, 58
	v_lshlrev_b64 v[44:45], 2, v[44:45]
	v_readlane_b32 s47, v253, 59
	s_nop 1
	v_lshl_add_u64 v[46:47], s[46:47], 0, v[44:45]
	v_readlane_b32 s46, v253, 60
	v_readlane_b32 s47, v253, 61
	s_nop 1
	v_lshl_add_u64 v[44:45], s[46:47], 0, v[44:45]
	global_store_dwordx4 v[46:47], v[28:31], off
	global_store_dwordx4 v[46:47], v[32:35], off offset:16
	global_store_dwordx4 v[44:45], v[20:23], off
	global_store_dwordx4 v[44:45], v[24:27], off offset:16

; #define LAS __attribute__((address_space(3)))
; __device__ __forceinline__ void attn_item(const Args& a, LAS unsigned char* lds, int layer, bool is_sample, int b, int c, int kvh, int seq_row0, int nchunks, bf16_t* proj, const int tid) {
;     ...
;         } else if (pos >= 0) {
;             const bf16_t* rp = proj + (size_t)(seq_row0 + pos) * PN;
;             const u32x4 kw = *(const u32x4*)(rp + C_K + kvh * 64 + oc * 8), vw = *(const u32x4*)(rp + C_V + kvh * 64 + oc * 8);
;             kf[0] = bflo(kw.x); kf[1] = bfhi(kw.x); kf[2] = bflo(kw.y); kf[3] = bfhi(kw.y); kf[4] = bflo(kw.z); kf[5] = bfhi(kw.z); kf[6] = bflo(kw.w); kf[7] = bfhi(kw.w);
;             vf[0] = bflo(vw.x); vf[1] = bfhi(vw.x); vf[2] = bflo(vw.y); vf[3] = bfhi(vw.y); vf[4] = bflo(vw.z); vf[5] = bfhi(vw.z); vf[6] = bflo(vw.w); vf[7] = bfhi(vw.w);
;             float ss = 0.f;
; #pragma unroll
;             for (int e = 0; e < 8; ++e) ss += kf[e] * kf[e];
;             ss += __shfl_xor(ss, 1); ss += __shfl_xor(ss, 2); ss += __shfl_xor(ss, 4);
;             const float rs = rsqrtf(ss * (1.f / 64.f) + EPS);
;             const f32x4 g0 = *(const f32x4*)(kng + oc * 8), g1 = *(const f32x4*)(kng + oc * 8 + 4);
; #pragma unroll
;             for (int e = 0; e < 4; ++e) { kf[e] = kf[e] * rs * g0[e]; kf[4 + e] = kf[4 + e] * rs * g1[e]; }
;             if (kl >= 128 && (is_sample || c >= nchunks - 2)) {
;                 const int orow = is_sample ? (kl - 128) : (c - (nchunks - 2)) * 64 + (kl - 128);
;                 const size_t nb_ = is_sample ? NSB : NPB; const int lr = is_sample ? DSEQ : 128;
;                 const size_t off = (((size_t)(layer * nb_ + b) * lr + orow) * NKVH + kvh) * 64 + oc * 8;
;                 float* ko = a.out + (is_sample ? O_KS : O_KP) + off; float* vo = a.out + (is_sample ? O_VS : O_VP) + off;
;                 *(f32x4*)ko = (f32x4){kf[0], kf[1], kf[2], kf[3]}; *(f32x4*)(ko + 4) = (f32x4){kf[4], kf[5], kf[6], kf[7]};
;                 *(f32x4*)vo = (f32x4){vf[0], vf[1], vf[2], vf[3]}; *(f32x4*)(vo + 4) = (f32x4){vf[4], vf[5], vf[6], vf[7]};
;     ...
;         u32x4 w; w.x = pk2(kf[0], kf[1]); w.y = pk2(kf[2], kf[3]); w.z = pk2(kf[4], kf[5]); w.w = pk2(kf[6], kf[7]);
;         *(LAS u32x4*)(lds + L_KS + kl * PK + oc * 16) = w;
; #pragma unroll
;         for (int e = 0; e < 8; ++e) *(LAS bf16_t*)(lds + L_VT + (oc * 8 + e) * PV + (kl ^ (oc << 2)) * 2) = f2bf(vf[e]);
.LBB0_459:
	s_or_b64 exec, exec, s[16:17]
	v_lshl_add_u32 v40, v19, 4, 0
	v_cvt_pk_bf16_f32 v28, v28, v29
	v_cvt_pk_bf16_f32 v29, v30, v31
	v_cvt_pk_bf16_f32 v30, v32, v33
	v_mad_u64_u32 v[32:33], s[4:5], v37, s74, v[40:41]
	v_cvt_pk_bf16_f32 v31, v34, v35
	ds_write_b128 v32, v[28:31]
	v_lshlrev_b32_e32 v28, 1, v37
	v_xor_b32_e32 v28, v28, v43
	v_mul_u32_u24_e32 v34, 0xc80, v19
	v_cvt_pk_bf16_f32 v20, v20, v1
	v_add3_u32 v19, 0, v28, v34
	ds_write_b16 v19, v20 offset:27648
	v_cvt_pk_bf16_f32 v20, v21, v1
	ds_write_b16 v19, v20 offset:28048
	v_cvt_pk_bf16_f32 v20, v22, v1
	ds_write_b16 v19, v20 offset:28448
	v_cvt_pk_bf16_f32 v20, v23, v1
	ds_write_b16 v19, v20 offset:28848
	v_cvt_pk_bf16_f32 v20, v24, v1
	ds_write_b16 v19, v20 offset:29248
	v_cvt_pk_bf16_f32 v20, v25, v1
	v_add_u32_e32 v37, 0x200, v36
	ds_write_b16 v19, v20 offset:29648
	v_cvt_pk_bf16_f32 v20, v26, v1
	v_ashrrev_i32_e32 v35, 3, v37
	ds_write_b16 v19, v20 offset:30048
	v_cvt_pk_bf16_f32 v20, v27, v1
	v_add_u32_e32 v44, s44, v35
	ds_write_b16 v19, v20 offset:30448
	v_cmp_lt_i32_e32 vcc, -1, v44
	v_mov_b32_e32 v19, 0
	v_mov_b32_e32 v20, 0
	v_mov_b32_e32 v21, 0
	v_mov_b32_e32 v22, 0
	v_mov_b32_e32 v23, 0
	v_mov_b32_e32 v24, 0
	v_mov_b32_e32 v25, 0
	v_mov_b32_e32 v26, 0
	v_mov_b32_e32 v27, 0
	v_mov_b32_e32 v28, 0
	v_mov_b32_e32 v29, 0
	v_mov_b32_e32 v30, 0
	v_mov_b32_e32 v31, 0
	v_mov_b32_e32 v32, 0
	v_mov_b32_e32 v33, 0
	s_and_saveexec_b64 s[16:17], vcc
	s_cbranch_execz .LBB0_463
	v_add_u32_e32 v20, s43, v44
	v_mov_b64_e32 v[18:19], s[18:19]
	v_mad_i64_i32 v[18:19], s[4:5], v20, s33, v[18:19]
	s_lshl_b32 s10, s41, 1
	v_lshl_add_u64 v[18:19], v[18:19], 0, s[10:11]
	v_lshl_add_u64 v[18:19], v[18:19], 0, v[0:1]
	v_add_co_u32_e32 v22, vcc, 0x3000, v18
	s_movk_i32 s4, 0x7f
	s_nop 0
	v_addc_co_u32_e32 v23, vcc, 0, v19, vcc
	s_waitcnt vmcnt(2)
	v_mov_b32_e32 v18, v216
	v_mov_b32_e32 v19, v217
	v_mov_b32_e32 v20, v218
	v_mov_b32_e32 v21, v219
	v_mov_b32_e32 v22, v220
	v_mov_b32_e32 v23, v221
	v_mov_b32_e32 v24, v222
	v_mov_b32_e32 v25, v223
	v_mov_b32_e32 v26, v232
	v_mov_b32_e32 v27, v233
	v_mov_b32_e32 v28, v234
	v_mov_b32_e32 v29, v235
	v_mov_b32_e32 v30, v236
	v_mov_b32_e32 v31, v237
	v_mov_b32_e32 v32, v238
	v_mov_b32_e32 v33, v239
	v_cmp_lt_i32_e32 vcc, v204, v203
	s_xor_b64 s[46:47], s[14:15], -1
	s_waitcnt vmcnt(3)
	v_lshlrev_b32_e32 v48, 16, v18
	v_and_b32_e32 v49, 0xffff0000, v18
	v_lshlrev_b32_e32 v50, 16, v19
	v_and_b32_e32 v51, 0xffff0000, v19
	v_pk_mul_f32 v[52:53], v[48:49], v[48:49]
	v_pk_mul_f32 v[54:55], v[50:51], v[50:51]
	v_add_f32_e32 v52, v52, v53
	v_cndmask_b32_e32 v44, v201, v204, vcc
	v_lshlrev_b32_e32 v46, 16, v20
	v_and_b32_e32 v47, 0xffff0000, v20
	v_add_f32_e32 v52, v54, v52
	v_lshlrev_b32_e32 v56, 2, v44
	v_and_b32_e32 v44, 0xffff0000, v21
	v_lshlrev_b32_e32 v45, 16, v21
	v_pk_mul_f32 v[20:21], v[46:47], v[46:47]
	v_add_f32_e32 v52, v55, v52
	v_add_f32_e32 v20, v20, v52
	v_pk_mul_f32 v[18:19], v[44:45], v[44:45]
	v_add_f32_e32 v20, v21, v20
	v_add_f32_e32 v19, v19, v20
	v_add_f32_e32 v18, v18, v19
	v_cmp_lt_i32_e32 vcc, s4, v35
	v_cmp_lt_i32_e64 s[4:5], v205, v203
	s_and_b64 s[46:47], vcc, s[46:47]
	s_waitcnt lgkmcnt(0)
	s_nop 1
	v_add_f32_dpp v19, v18, v18 quad_perm:[1,0,3,2] row_mask:0xf bank_mask:0xf
	v_cndmask_b32_e64 v20, v201, v205, s[4:5]
	v_lshlrev_b32_e32 v20, 2, v20
	v_cmp_lt_i32_e64 s[4:5], v206, v203
	s_waitcnt lgkmcnt(0)
	s_nop 1
	v_add_f32_dpp v52, v19, v19 quad_perm:[2,3,0,1] row_mask:0xf bank_mask:0xf
	v_cndmask_b32_e64 v18, v201, v206, s[4:5]
	v_lshlrev_b32_e32 v21, 2, v18
	s_waitcnt vmcnt(2)
	v_lshlrev_b32_e32 v20, 16, v23
	v_and_b32_e32 v21, 0xffff0000, v23
	s_mov_b32 s4, 0x800000
	v_lshlrev_b32_e32 v18, 16, v22
	s_waitcnt lgkmcnt(0)
	s_nop 1
	v_add_f32_dpp v23, v52, v52 row_half_mirror row_mask:0xf bank_mask:0xf
	v_fmamk_f32 v23, v23, 0x3c800000, v167
	v_mul_f32_e32 v52, 0x4b800000, v23
	v_cmp_gt_f32_e64 s[4:5], s4, v23
	v_and_b32_e32 v19, 0xffff0000, v22
	v_lshlrev_b32_e32 v22, 16, v24
	v_cndmask_b32_e64 v23, v23, v52, s[4:5]
	v_rsq_f32_e32 v52, v23
	v_and_b32_e32 v23, 0xffff0000, v24
	v_lshlrev_b32_e32 v24, 16, v25
	v_and_b32_e32 v25, 0xffff0000, v25
	v_mul_f32_e32 v53, 0x45800000, v52
	v_cndmask_b32_e64 v52, v52, v53, s[4:5]
	v_pk_mul_f32 v[48:49], v[52:53], v[48:49] op_sel_hi:[0,1]
	v_pk_mul_f32 v[46:47], v[52:53], v[46:47] op_sel_hi:[0,1]
	v_pk_mul_f32 v[50:51], v[52:53], v[50:51] op_sel_hi:[0,1]
	v_pk_mul_f32 v[44:45], v[52:53], v[44:45] op_sel_hi:[0,1]
	s_waitcnt vmcnt(1)
	v_pk_mul_f32 v[26:27], v[26:27], v[48:49]
	s_waitcnt vmcnt(0)
	v_pk_mul_f32 v[30:31], v[30:31], v[46:47]
	v_pk_mul_f32 v[28:29], v[28:29], v[50:51]
	v_pk_mul_f32 v[32:33], v[32:33], v[44:45] op_sel:[0,1] op_sel_hi:[1,0]
	s_and_saveexec_b64 s[4:5], s[46:47]
	s_cbranch_execz .LBB0_462
	s_lshl_b64 s[46:47], s[6:7], 7
	v_readlane_b32 s48, v255, 16
	v_add_u32_e32 v44, s42, v35
	v_readlane_b32 s49, v255, 17
	s_add_u32 s46, s46, s48
	s_addc_u32 s47, s47, s49
	v_ashrrev_i32_e32 v45, 31, v44
	v_lshl_add_u64 v[44:45], s[46:47], 0, v[44:45]
	v_lshlrev_b64 v[44:45], 8, v[44:45]
	v_or3_b32 v45, v45, 0, 0
	v_or3_b32 v44, v44, v43, s41
	v_readlane_b32 s46, v253, 58
	v_lshlrev_b64 v[44:45], 2, v[44:45]
	v_readlane_b32 s47, v253, 59
	s_nop 1
	v_lshl_add_u64 v[46:47], s[46:47], 0, v[44:45]
	v_readlane_b32 s46, v253, 60
	v_readlane_b32 s47, v253, 61
	s_nop 1
	v_lshl_add_u64 v[44:45], s[46:47], 0, v[44:45]
	global_store_dwordx4 v[46:47], v[26:29], off
	global_store_dwordx4 v[46:47], v[30:33], off offset:16
	global_store_dwordx4 v[44:45], v[18:21], off
	global_store_dwordx4 v[44:45], v[22:25], off offset:16

; #define LAS __attribute__((address_space(3)))
; __device__ __forceinline__ void attn_item(const Args& a, LAS unsigned char* lds, int layer, bool is_sample, int b, int c, int kvh, int seq_row0, int nchunks, bf16_t* proj, const int tid) {
;     ...
;         } else if (pos >= 0) {
;             const bf16_t* rp = proj + (size_t)(seq_row0 + pos) * PN;
;             const u32x4 kw = *(const u32x4*)(rp + C_K + kvh * 64 + oc * 8), vw = *(const u32x4*)(rp + C_V + kvh * 64 + oc * 8);
;             kf[0] = bflo(kw.x); kf[1] = bfhi(kw.x); kf[2] = bflo(kw.y); kf[3] = bfhi(kw.y); kf[4] = bflo(kw.z); kf[5] = bfhi(kw.z); kf[6] = bflo(kw.w); kf[7] = bfhi(kw.w);
;             vf[0] = bflo(vw.x); vf[1] = bfhi(vw.x); vf[2] = bflo(vw.y); vf[3] = bfhi(vw.y); vf[4] = bflo(vw.z); vf[5] = bfhi(vw.z); vf[6] = bflo(vw.w); vf[7] = bfhi(vw.w);
;             float ss = 0.f;
; #pragma unroll
;             for (int e = 0; e < 8; ++e) ss += kf[e] * kf[e];
;             ss += __shfl_xor(ss, 1); ss += __shfl_xor(ss, 2); ss += __shfl_xor(ss, 4);
;             const float rs = rsqrtf(ss * (1.f / 64.f) + EPS);
;             const f32x4 g0 = *(const f32x4*)(kng + oc * 8), g1 = *(const f32x4*)(kng + oc * 8 + 4);
; #pragma unroll
;             for (int e = 0; e < 4; ++e) { kf[e] = kf[e] * rs * g0[e]; kf[4 + e] = kf[4 + e] * rs * g1[e]; }
;             if (kl >= 128 && (is_sample || c >= nchunks - 2)) {
;                 const int orow = is_sample ? (kl - 128) : (c - (nchunks - 2)) * 64 + (kl - 128);
;                 const size_t nb_ = is_sample ? NSB : NPB; const int lr = is_sample ? DSEQ : 128;
;                 const size_t off = (((size_t)(layer * nb_ + b) * lr + orow) * NKVH + kvh) * 64 + oc * 8;
;                 float* ko = a.out + (is_sample ? O_KS : O_KP) + off; float* vo = a.out + (is_sample ? O_VS : O_VP) + off;
;                 *(f32x4*)ko = (f32x4){kf[0], kf[1], kf[2], kf[3]}; *(f32x4*)(ko + 4) = (f32x4){kf[4], kf[5], kf[6], kf[7]};
;                 *(f32x4*)vo = (f32x4){vf[0], vf[1], vf[2], vf[3]}; *(f32x4*)(vo + 4) = (f32x4){vf[4], vf[5], vf[6], vf[7]};
;     ...
;         u32x4 w; w.x = pk2(kf[0], kf[1]); w.y = pk2(kf[2], kf[3]); w.z = pk2(kf[4], kf[5]); w.w = pk2(kf[6], kf[7]);
;         *(LAS u32x4*)(lds + L_KS + kl * PK + oc * 16) = w;
; #pragma unroll
;         for (int e = 0; e < 8; ++e) *(LAS bf16_t*)(lds + L_VT + (oc * 8 + e) * PV + (kl ^ (oc << 2)) * 2) = f2bf(vf[e]);
.LBB0_463:
	s_or_b64 exec, exec, s[16:17]
	v_cvt_pk_bf16_f32 v26, v26, v27
	v_cvt_pk_bf16_f32 v27, v28, v29
	v_cvt_pk_bf16_f32 v28, v30, v31
	v_mad_u64_u32 v[30:31], s[4:5], v35, s74, v[40:41]
	v_cvt_pk_bf16_f32 v29, v32, v33
	ds_write_b128 v30, v[26:29]
	v_lshlrev_b32_e32 v26, 1, v35
	v_xor_b32_e32 v26, v26, v43
	v_cvt_pk_bf16_f32 v18, v18, v1
	v_add3_u32 v26, 0, v26, v34
	ds_write_b16 v26, v18 offset:27648
	v_cvt_pk_bf16_f32 v18, v19, v1
	ds_write_b16 v26, v18 offset:28048
	v_cvt_pk_bf16_f32 v18, v20, v1
	ds_write_b16 v26, v18 offset:28448
	v_cvt_pk_bf16_f32 v18, v21, v1
	ds_write_b16 v26, v18 offset:28848
	v_cvt_pk_bf16_f32 v18, v22, v1
	ds_write_b16 v26, v18 offset:29248
	v_cvt_pk_bf16_f32 v18, v23, v1
	ds_write_b16 v26, v18 offset:29648
	v_cvt_pk_bf16_f32 v18, v24, v1
	ds_write_b16 v26, v18 offset:30048
	v_cvt_pk_bf16_f32 v18, v25, v1
	ds_write_b16 v26, v18 offset:30448
	v_add_u32_e32 v18, 0x400, v36
	v_ashrrev_i32_e32 v35, 3, v18
	v_add_u32_e32 v44, s44, v35
	v_mov_b32_e32 v18, 0
	v_cmp_lt_i32_e32 vcc, -1, v44
	v_mov_b32_e32 v19, 0
	v_mov_b32_e32 v20, 0
	v_mov_b32_e32 v21, 0
	v_mov_b32_e32 v22, 0
	v_mov_b32_e32 v23, 0
	v_mov_b32_e32 v24, 0
	v_mov_b32_e32 v25, 0
	v_mov_b32_e32 v26, 0
	v_mov_b32_e32 v27, v18
	v_mov_b32_e32 v28, 0
	v_mov_b32_e32 v29, v18
	v_mov_b32_e32 v30, 0
	v_mov_b32_e32 v31, v18
	v_mov_b32_e32 v32, 0
	v_mov_b32_e32 v33, v18
	s_and_saveexec_b64 s[16:17], vcc
	s_cbranch_execz .LBB0_467
	v_add_u32_e32 v20, s43, v44
	v_mov_b64_e32 v[18:19], s[18:19]
	v_mad_i64_i32 v[18:19], s[4:5], v20, s33, v[18:19]
	s_lshl_b32 s10, s41, 1
	v_lshl_add_u64 v[18:19], v[18:19], 0, s[10:11]
	v_lshl_add_u64 v[18:19], v[18:19], 0, v[0:1]
	v_add_co_u32_e32 v22, vcc, 0x3000, v18
	s_movk_i32 s4, 0x7f
	s_nop 0
	v_addc_co_u32_e32 v23, vcc, 0, v19, vcc
	s_waitcnt vmcnt(0)
	v_mov_b32_e32 v18, v224
	v_mov_b32_e32 v19, v225
	v_mov_b32_e32 v20, v226
	v_mov_b32_e32 v21, v227
	v_mov_b32_e32 v22, v228
	v_mov_b32_e32 v23, v229
	v_mov_b32_e32 v24, v230
	v_mov_b32_e32 v25, v231
	v_mov_b32_e32 v26, v232
	v_mov_b32_e32 v27, v233
	v_mov_b32_e32 v28, v234
	v_mov_b32_e32 v29, v235
	v_mov_b32_e32 v30, v236
	v_mov_b32_e32 v31, v237
	v_mov_b32_e32 v32, v238
	v_mov_b32_e32 v33, v239
	v_cmp_lt_i32_e32 vcc, v204, v203
	s_xor_b64 s[14:15], s[14:15], -1
	s_waitcnt vmcnt(3)
	v_lshlrev_b32_e32 v46, 16, v18
	v_and_b32_e32 v47, 0xffff0000, v18
	v_lshlrev_b32_e32 v48, 16, v19
	v_and_b32_e32 v49, 0xffff0000, v19
	v_pk_mul_f32 v[50:51], v[46:47], v[46:47]
	v_pk_mul_f32 v[52:53], v[48:49], v[48:49]
	v_add_f32_e32 v50, v50, v51
	v_lshlrev_b32_e32 v44, 16, v20
	v_and_b32_e32 v45, 0xffff0000, v20
	v_add_f32_e32 v50, v52, v50
	v_and_b32_e32 v38, 0xffff0000, v21
	v_lshlrev_b32_e32 v39, 16, v21
	v_pk_mul_f32 v[20:21], v[44:45], v[44:45]
	v_add_f32_e32 v50, v53, v50
	v_add_f32_e32 v20, v20, v50
	v_pk_mul_f32 v[18:19], v[38:39], v[38:39]
	v_add_f32_e32 v20, v21, v20
	v_cndmask_b32_e32 v0, v201, v204, vcc
	v_add_f32_e32 v19, v19, v20
	v_lshlrev_b32_e32 v0, 2, v0
	v_add_f32_e32 v18, v18, v19
	v_cmp_lt_i32_e32 vcc, s4, v35
	v_cmp_lt_i32_e64 s[4:5], v205, v203
	s_waitcnt vmcnt(2)
	v_and_b32_e32 v21, 0xffff0000, v23
	s_and_b64 s[14:15], vcc, s[14:15]
	v_cndmask_b32_e64 v19, v201, v205, s[4:5]
	v_lshlrev_b32_e32 v19, 2, v19
	s_waitcnt lgkmcnt(0)
	s_nop 1
	v_add_f32_dpp v0, v18, v18 quad_perm:[1,0,3,2] row_mask:0xf bank_mask:0xf
	v_cmp_lt_i32_e64 s[4:5], v206, v203
	s_waitcnt lgkmcnt(0)
	s_nop 1
	v_add_f32_dpp v0, v0, v0 quad_perm:[2,3,0,1] row_mask:0xf bank_mask:0xf
	v_cndmask_b32_e64 v18, v201, v206, s[4:5]
	v_lshlrev_b32_e32 v20, 2, v18
	s_mov_b32 s4, 0x800000
	v_lshlrev_b32_e32 v20, 16, v23
	v_lshlrev_b32_e32 v18, 16, v22
	v_and_b32_e32 v19, 0xffff0000, v22
	s_waitcnt lgkmcnt(0)
	s_nop 1
	v_add_f32_dpp v0, v0, v0 row_half_mirror row_mask:0xf bank_mask:0xf
	v_fmamk_f32 v0, v0, 0x3c800000, v167
	v_mul_f32_e32 v23, 0x4b800000, v0
	v_cmp_gt_f32_e64 s[4:5], s4, v0
	v_lshlrev_b32_e32 v22, 16, v24
	s_nop 0
	v_cndmask_b32_e64 v0, v0, v23, s[4:5]
	v_rsq_f32_e32 v0, v0
	v_and_b32_e32 v23, 0xffff0000, v24
	v_lshlrev_b32_e32 v24, 16, v25
	v_and_b32_e32 v25, 0xffff0000, v25
	v_mul_f32_e32 v50, 0x45800000, v0
	v_cndmask_b32_e64 v0, v0, v50, s[4:5]
	v_pk_mul_f32 v[46:47], v[0:1], v[46:47] op_sel_hi:[0,1]
	v_pk_mul_f32 v[44:45], v[0:1], v[44:45] op_sel_hi:[0,1]
	v_pk_mul_f32 v[48:49], v[0:1], v[48:49] op_sel_hi:[0,1]
	v_pk_mul_f32 v[38:39], v[0:1], v[38:39] op_sel_hi:[0,1]
	s_waitcnt vmcnt(1)
	v_pk_mul_f32 v[26:27], v[26:27], v[46:47]
	s_waitcnt vmcnt(0)
	v_pk_mul_f32 v[30:31], v[30:31], v[44:45]
	v_pk_mul_f32 v[28:29], v[28:29], v[48:49]
	v_pk_mul_f32 v[32:33], v[32:33], v[38:39] op_sel:[0,1] op_sel_hi:[1,0]
	s_and_saveexec_b64 s[4:5], s[14:15]
	s_cbranch_execz .LBB0_466
	s_lshl_b64 s[6:7], s[6:7], 7
	v_readlane_b32 s14, v255, 16
	v_add_u32_e32 v38, s42, v35
	v_readlane_b32 s15, v255, 17
	s_add_u32 s6, s6, s14
	s_addc_u32 s7, s7, s15
	v_ashrrev_i32_e32 v39, 31, v38
	v_lshl_add_u64 v[38:39], s[6:7], 0, v[38:39]
	v_lshlrev_b64 v[38:39], 8, v[38:39]
	v_or3_b32 v39, v39, 0, 0
	v_or3_b32 v38, v38, v43, s41
	v_readlane_b32 s6, v253, 58
	v_lshlrev_b64 v[38:39], 2, v[38:39]
	v_readlane_b32 s7, v253, 59
	s_nop 1
	v_lshl_add_u64 v[44:45], s[6:7], 0, v[38:39]
	v_readlane_b32 s6, v253, 60
	v_readlane_b32 s7, v253, 61
	s_nop 1
	v_lshl_add_u64 v[38:39], s[6:7], 0, v[38:39]
	global_store_dwordx4 v[44:45], v[26:29], off
	global_store_dwordx4 v[44:45], v[30:33], off offset:16
	global_store_dwordx4 v[38:39], v[18:21], off
	global_store_dwordx4 v[38:39], v[22:25], off offset:16

; __device__ __forceinline__ unsigned pk2(float lo, float hi) { unsigned r; asm("v_cvt_pk_bf16_f32 %0, %1, %2" : "=v"(r) : "v"(lo), "v"(hi)); return r; }
; __device__ __forceinline__ void attn_item(const Args& a, LAS unsigned char* lds, int layer, bool is_sample, int b, int c, int kvh, int seq_row0, int nchunks, bf16_t* proj, const int tid) {
;     ...
;         float mx = sink;
; #pragma unroll
;         for (int kb = 0; kb < 12; ++kb)
; #pragma unroll
;             for (int j = 0; j < 4; ++j) { const int kl = 16 * kb + 4 * fq + j;
;                 const float s = sacc[kb][j] + bt[g * 256 + kl - 128 - ql + 191];
;                 sacc[kb][j] = s; mx = fmaxf(mx, s); }
;         if (kmin > 0) {
;             mx = sink;
; #pragma unroll
;             for (int kb = 0; kb < 12; ++kb)
; #pragma unroll
;                 for (int j = 0; j < 4; ++j) { const int kl = 16 * kb + 4 * fq + j; if (kl < kmin) sacc[kb][j] = -INFINITY; mx = fmaxf(mx, sacc[kb][j]); }
;         }
;         mx = fmaxf(mx, __shfl_xor(mx, 16)); mx = fmaxf(mx, __shfl_xor(mx, 32));
;         float sum = 0.f;
; #pragma unroll
;         for (int kb = 0; kb < 12; ++kb)
; #pragma unroll
;             for (int j = 0; j < 4; ++j) { const float p = __builtin_amdgcn_exp2f(sacc[kb][j] - mx); sacc[kb][j] = p; sum += p; }
;         sum += __shfl_xor(sum, 16); sum += __shfl_xor(sum, 32);
;         const float inv = __builtin_amdgcn_rcpf(sum + __builtin_amdgcn_exp2f(sink - mx));
;         f32x4 oacc[4];
; #pragma unroll
;         for (int db = 0; db < 4; ++db) oacc[db] = (f32x4){0.f, 0.f, 0.f, 0.f};
; #pragma unroll
;         for (int ks = 0; ks < 6; ++ks) {
;             u32x4 pw; pw.x = pk2(sacc[2 * ks][0], sacc[2 * ks][1]); pw.y = pk2(sacc[2 * ks][2], sacc[2 * ks][3]); pw.z = pk2(sacc[2 * ks + 1][0], sacc[2 * ks + 1][1]); pw.w = pk2(sacc[2 * ks + 1][2], sacc[2 * ks + 1][3]);
.LBB0_476:
	s_waitcnt lgkmcnt(1)
	v_add_f32_e32 v31, v18, v76
	v_add_f32_e32 v19, v19, v77
	v_add_f32_e32 v20, v20, v78
	v_add_f32_e32 v21, v21, v79
	v_max3_f32 v18, v147, v31, v19
	v_add_f32_e32 v22, v22, v80
	v_add_f32_e32 v23, v23, v81
	v_max3_f32 v18, v18, v20, v21
	v_add_f32_e32 v24, v24, v82
	v_add_f32_e32 v41, v25, v83
	v_max3_f32 v18, v18, v22, v23
	v_add_f32_e32 v43, v26, v84
	v_add_f32_e32 v76, v27, v85
	v_max3_f32 v18, v18, v24, v41
	v_add_f32_e32 v77, v28, v86
	v_add_f32_e32 v78, v29, v87
	v_max3_f32 v18, v18, v43, v76
	v_add_f32_e32 v79, v32, v88
	v_add_f32_e32 v80, v33, v89
	v_max3_f32 v18, v18, v77, v78
	s_waitcnt lgkmcnt(0)
	v_add_f32_e32 v81, v34, v90
	v_add_f32_e32 v82, v35, v91
	v_max3_f32 v18, v18, v79, v80
	v_max3_f32 v18, v18, v81, v82
	s_xor_b64 s[16:17], s[16:17], -1
	s_mov_b32 s10, 16
	s_waitcnt lgkmcnt(0)
	v_mov_b32_e32 v25, v18
	v_mov_b32_e32 v250, v18
	s_nop 1
	v_permlane16_swap_b32_e32 v25, v250
	v_max_f32_e32 v25, v25, v250
	v_max_f32_e32 v18, v18, v25
	s_waitcnt lgkmcnt(0)
	v_mov_b32_e32 v25, v18
	v_mov_b32_e32 v250, v18
	s_nop 1
	v_permlane32_swap_b32_e32 v25, v250
	v_max_f32_e32 v25, v25, v250
	v_max_f32_e32 v18, v18, v25
	v_sub_f32_e32 v25, v68, v18
	v_exp_f32_e32 v25, v25
	v_sub_f32_e32 v27, v69, v18
	v_exp_f32_e32 v27, v27
	v_sub_f32_e32 v28, v30, v18
	v_exp_f32_e32 v28, v28
	v_sub_f32_e32 v29, v70, v18
	v_exp_f32_e32 v29, v29
	v_sub_f32_e32 v30, v62, v18
	v_add_f32_e32 v26, 0, v25
	v_exp_f32_e32 v32, v30
	v_sub_f32_e32 v30, v63, v18
	v_add_f32_e32 v26, v27, v26
	v_exp_f32_e32 v33, v30
	v_sub_f32_e32 v30, v36, v18
	v_add_f32_e32 v26, v28, v26
	v_exp_f32_e32 v34, v30
	v_sub_f32_e32 v30, v71, v18
	v_add_f32_e32 v26, v29, v26
	v_exp_f32_e32 v35, v30
	v_sub_f32_e32 v30, v64, v18
	v_add_f32_e32 v26, v32, v26
	v_exp_f32_e32 v45, v30
	v_sub_f32_e32 v30, v65, v18
	v_add_f32_e32 v26, v33, v26
	v_exp_f32_e32 v47, v30
	v_sub_f32_e32 v30, v38, v18
	v_add_f32_e32 v26, v34, v26
	v_exp_f32_e32 v49, v30
	v_sub_f32_e32 v30, v72, v18
	v_add_f32_e32 v26, v35, v26
	v_exp_f32_e32 v62, v30
	v_sub_f32_e32 v30, v58, v18
	v_add_f32_e32 v26, v45, v26
	v_exp_f32_e32 v58, v30
	v_sub_f32_e32 v30, v59, v18
	v_add_f32_e32 v26, v47, v26
	v_exp_f32_e32 v59, v30
	v_sub_f32_e32 v30, v40, v18
	v_add_f32_e32 v26, v49, v26
	v_exp_f32_e32 v63, v30
	v_sub_f32_e32 v30, v73, v18
	v_add_f32_e32 v26, v62, v26
	v_exp_f32_e32 v64, v30
	v_sub_f32_e32 v30, v60, v18
	v_add_f32_e32 v26, v58, v26
	v_exp_f32_e32 v60, v30
	v_sub_f32_e32 v30, v61, v18
	v_add_f32_e32 v26, v59, v26
	v_exp_f32_e32 v61, v30
	v_sub_f32_e32 v30, v42, v18
	v_add_f32_e32 v26, v63, v26
	v_exp_f32_e32 v65, v30
	v_sub_f32_e32 v30, v74, v18
	v_add_f32_e32 v26, v64, v26
	v_exp_f32_e32 v69, v30
	v_sub_f32_e32 v30, v54, v18
	v_add_f32_e32 v26, v60, v26
	v_exp_f32_e32 v54, v30
	v_sub_f32_e32 v30, v55, v18
	v_add_f32_e32 v26, v61, v26
	v_exp_f32_e32 v55, v30
	v_sub_f32_e32 v30, v44, v18
	v_add_f32_e32 v26, v65, v26
	v_exp_f32_e32 v70, v30
	v_sub_f32_e32 v30, v75, v18
	v_add_f32_e32 v26, v69, v26
	v_exp_f32_e32 v71, v30
	v_sub_f32_e32 v30, v56, v18
	v_add_f32_e32 v26, v54, v26
	v_exp_f32_e32 v56, v30
	v_sub_f32_e32 v30, v57, v18
	v_add_f32_e32 v26, v55, v26
	v_exp_f32_e32 v57, v30
	v_sub_f32_e32 v30, v46, v18
	v_add_f32_e32 v26, v70, v26
	v_exp_f32_e32 v72, v30
	v_sub_f32_e32 v30, v52, v18
	v_add_f32_e32 v26, v71, v26
	v_exp_f32_e32 v52, v30
	v_sub_f32_e32 v30, v50, v18
	v_add_f32_e32 v26, v56, v26
	v_exp_f32_e32 v73, v30
	v_sub_f32_e32 v30, v51, v18
	v_add_f32_e32 v26, v57, v26
	v_exp_f32_e32 v74, v30
	v_sub_f32_e32 v30, v48, v18
	v_add_f32_e32 v26, v72, v26
	v_exp_f32_e32 v75, v30
	v_sub_f32_e32 v30, v53, v18
	v_add_f32_e32 v26, v52, v26
	v_exp_f32_e32 v53, v30
	v_sub_f32_e32 v30, v31, v18
	v_add_f32_e32 v26, v73, v26
	v_exp_f32_e32 v83, v30
	v_sub_f32_e32 v19, v19, v18
	v_add_f32_e32 v26, v74, v26
	v_exp_f32_e32 v19, v19
	v_sub_f32_e32 v20, v20, v18
	v_add_f32_e32 v26, v75, v26
	v_exp_f32_e32 v84, v20
	v_sub_f32_e32 v20, v21, v18
	v_add_f32_e32 v26, v53, v26
	v_exp_f32_e32 v85, v20
	v_sub_f32_e32 v20, v22, v18
	v_add_f32_e32 v26, v83, v26
	v_exp_f32_e32 v86, v20
	v_add_f32_e32 v20, v19, v26
	v_add_f32_e32 v20, v84, v20
	v_add_f32_e32 v20, v85, v20
	v_add_f32_e32 v40, v86, v20
	v_sub_f32_e32 v20, v23, v18
	v_sub_f32_e32 v36, v24, v18
	v_exp_f32_e32 v87, v20
	ds_read_b64 v[20:21], v98 offset:27648
	ds_read_b64 v[22:23], v99 offset:27648
	v_cvt_pk_bf16_f32 v24, v25, v27
	v_cvt_pk_bf16_f32 v25, v28, v29
	ds_read_b64 v[28:29], v100 offset:34048
	ds_read_b64 v[30:31], v101 offset:34048
	v_cvt_pk_bf16_f32 v26, v32, v33
	v_cvt_pk_bf16_f32 v27, v34, v35
	ds_read_b64 v[32:33], v102 offset:40448
	ds_read_b64 v[34:35], v103 offset:40448
	v_exp_f32_e32 v88, v36
	ds_read_b64 v[36:37], v104 offset:46848
	ds_read_b64 v[38:39], v105 offset:46848
	s_waitcnt lgkmcnt(6)
	v_mfma_f32_16x16x32_bf16 v[20:23], v[20:23], v[24:27], 0
	v_sub_f32_e32 v41, v41, v18
	v_exp_f32_e32 v89, v41
	v_add_f32_e32 v40, v87, v40
	s_waitcnt lgkmcnt(4)
	v_mfma_f32_16x16x32_bf16 v[28:31], v[28:31], v[24:27], 0
	v_add_f32_e32 v40, v88, v40
	v_add_f32_e32 v90, v89, v40
	v_sub_f32_e32 v91, v43, v18
	s_waitcnt lgkmcnt(2)
	v_mfma_f32_16x16x32_bf16 v[32:35], v[32:35], v[24:27], 0
	v_cvt_pk_bf16_f32 v40, v45, v47
	v_cvt_pk_bf16_f32 v41, v49, v62
	v_cvt_pk_bf16_f32 v42, v58, v59
	s_waitcnt lgkmcnt(0)
	v_mfma_f32_16x16x32_bf16 v[24:27], v[36:39], v[24:27], 0
	ds_read_b64 v[36:37], v106 offset:27648
	ds_read_b64 v[38:39], v107 offset:27648
	ds_read_b64 v[44:45], v108 offset:34048
	ds_read_b64 v[46:47], v109 offset:34048
	v_cvt_pk_bf16_f32 v43, v63, v64
	ds_read_b64 v[48:49], v110 offset:40448
	ds_read_b64 v[50:51], v111 offset:40448
	s_waitcnt lgkmcnt(4)
; #define LAS __attribute__((address_space(3)))
; __device__ __forceinline__ unsigned pk2(float lo, float hi) { unsigned r; asm("v_cvt_pk_bf16_f32 %0, %1, %2" : "=v"(r) : "v"(lo), "v"(hi)); return r; }
; __device__ __forceinline__ f32x4 mfma16(bf16x8 a, bf16x8 b, f32x4 c) { return __builtin_amdgcn_mfma_f32_16x16x32_bf16(a, b, c, 0, 0, 0); }
; __device__ __forceinline__ void attn_item(const Args& a, LAS unsigned char* lds, int layer, bool is_sample, int b, int c, int kvh, int seq_row0, int nchunks, bf16_t* proj, const int tid) {
;     ...
;             for (int j = 0; j < 4; ++j) { const float p = __builtin_amdgcn_exp2f(sacc[kb][j] - mx); sacc[kb][j] = p; sum += p; }
;         sum += __shfl_xor(sum, 16); sum += __shfl_xor(sum, 32);
;         const float inv = __builtin_amdgcn_rcpf(sum + __builtin_amdgcn_exp2f(sink - mx));
;         f32x4 oacc[4];
; #pragma unroll
;         for (int db = 0; db < 4; ++db) oacc[db] = (f32x4){0.f, 0.f, 0.f, 0.f};
; #pragma unroll
;         for (int ks = 0; ks < 6; ++ks) {
;             u32x4 pw; pw.x = pk2(sacc[2 * ks][0], sacc[2 * ks][1]); pw.y = pk2(sacc[2 * ks][2], sacc[2 * ks][3]); pw.z = pk2(sacc[2 * ks + 1][0], sacc[2 * ks + 1][1]); pw.w = pk2(sacc[2 * ks + 1][2], sacc[2 * ks + 1][3]);
;             const bf16x8 pbv = __builtin_bit_cast(bf16x8, pw);
; #pragma unroll
;             for (int db = 0; db < 4; ++db) { const LAS unsigned char* vr = lds + L_VT + (16 * db + fr) * PV; const int vkey = ((2 * db + (fr >> 3)) & 7) << 2;
;                 const u32x2 lo = *(const LAS u32x2*)(vr + ((32 * ks + 4 * fq) ^ vkey) * 2), hi = *(const LAS u32x2*)(vr + ((32 * ks + 16 + 4 * fq) ^ vkey) * 2);
;                 u32x4 vw; vw.x = lo.x; vw.y = lo.y; vw.z = hi.x; vw.w = hi.y;
;                 oacc[db] = mfma16(__builtin_bit_cast(bf16x8, vw), pbv, oacc[db]); }
;         }
; #pragma unroll
;         for (int db = 0; db < 4; ++db) { u32x2 w; w.x = pk2(oacc[db][0] * inv, oacc[db][1] * inv); w.y = pk2(oacc[db][2] * inv, oacc[db][3] * inv);
;             *(u32x2*)(qp + 16 * db + 4 * fq) = w; }
	v_mfma_f32_16x16x32_bf16 v[20:23], v[36:39], v[40:43], v[20:23]
	ds_read_b64 v[36:37], v112 offset:46848
	ds_read_b64 v[38:39], v113 offset:46848
	v_exp_f32_e32 v58, v91
	v_sub_f32_e32 v64, v78, v18
	s_waitcnt lgkmcnt(4)
	v_mfma_f32_16x16x32_bf16 v[28:31], v[44:47], v[40:43], v[28:31]
	v_sub_f32_e32 v44, v76, v18
	v_exp_f32_e32 v62, v44
	v_sub_f32_e32 v44, v77, v18
	s_waitcnt lgkmcnt(0)
	v_mfma_f32_16x16x32_bf16 v[24:27], v[36:39], v[40:43], v[24:27]
	ds_read_b64 v[36:37], v114 offset:27648
	ds_read_b64 v[38:39], v115 offset:27648
	v_exp_f32_e32 v63, v44
	ds_read_b64 v[44:45], v116 offset:34048
	ds_read_b64 v[46:47], v117 offset:34048
	v_mfma_f32_16x16x32_bf16 v[32:35], v[48:51], v[40:43], v[32:35]
	v_cvt_pk_bf16_f32 v40, v60, v61
	v_cvt_pk_bf16_f32 v41, v65, v69
	v_cvt_pk_bf16_f32 v42, v54, v55
	v_cvt_pk_bf16_f32 v43, v70, v71
	ds_read_b64 v[48:49], v118 offset:40448
	ds_read_b64 v[50:51], v119 offset:40448
	s_waitcnt lgkmcnt(4)
	v_mfma_f32_16x16x32_bf16 v[20:23], v[36:39], v[40:43], v[20:23]
	v_exp_f32_e32 v54, v64
	ds_read_b64 v[36:37], v120 offset:46848
	ds_read_b64 v[38:39], v121 offset:46848
	v_add_f32_e32 v59, v58, v90
	s_waitcnt lgkmcnt(4)
	v_mfma_f32_16x16x32_bf16 v[28:31], v[44:47], v[40:43], v[28:31]
	v_add_f32_e32 v44, v62, v59
	v_add_f32_e32 v44, v63, v44
	v_add_f32_e32 v55, v54, v44
	v_sub_f32_e32 v44, v79, v18
	v_exp_f32_e32 v59, v44
	s_waitcnt lgkmcnt(0)
	v_mfma_f32_16x16x32_bf16 v[24:27], v[36:39], v[40:43], v[24:27]
	ds_read_b64 v[36:37], v122 offset:27648
	ds_read_b64 v[38:39], v123 offset:27648
	ds_read_b64 v[44:45], v124 offset:34048
	ds_read_b64 v[46:47], v125 offset:34048
	v_sub_f32_e32 v60, v80, v18
	v_mfma_f32_16x16x32_bf16 v[32:35], v[48:51], v[40:43], v[32:35]
	v_cvt_pk_bf16_f32 v40, v56, v57
	v_cvt_pk_bf16_f32 v41, v72, v52
	v_cvt_pk_bf16_f32 v42, v73, v74
	v_cvt_pk_bf16_f32 v43, v75, v53
	ds_read_b64 v[48:49], v126 offset:40448
	ds_read_b64 v[50:51], v127 offset:40448
	s_waitcnt lgkmcnt(4)
	v_mfma_f32_16x16x32_bf16 v[20:23], v[36:39], v[40:43], v[20:23]
	v_exp_f32_e32 v56, v60
	ds_read_b64 v[36:37], v128 offset:46848
	ds_read_b64 v[38:39], v129 offset:46848
	v_sub_f32_e32 v53, v82, v18
	s_waitcnt lgkmcnt(4)
	v_mfma_f32_16x16x32_bf16 v[28:31], v[44:47], v[40:43], v[28:31]
	v_sub_f32_e32 v44, v81, v18
	v_exp_f32_e32 v57, v44
	v_add_f32_e32 v44, v59, v55
	v_add_f32_e32 v44, v56, v44
	s_waitcnt lgkmcnt(0)
	v_mfma_f32_16x16x32_bf16 v[24:27], v[36:39], v[40:43], v[24:27]
	v_add_f32_e32 v52, v57, v44
	ds_read_b64 v[36:37], v130 offset:27648
	ds_read_b64 v[38:39], v131 offset:27648
	ds_read_b64 v[44:45], v132 offset:34048
	ds_read_b64 v[46:47], v133 offset:34048
	v_mfma_f32_16x16x32_bf16 v[32:35], v[48:51], v[40:43], v[32:35]
	v_cvt_pk_bf16_f32 v40, v83, v19
	v_exp_f32_e32 v19, v53
	v_cvt_pk_bf16_f32 v41, v84, v85
	v_cvt_pk_bf16_f32 v42, v86, v87
	v_cvt_pk_bf16_f32 v43, v88, v89
	ds_read_b64 v[48:49], v134 offset:40448
	ds_read_b64 v[50:51], v135 offset:40448
	s_waitcnt lgkmcnt(2)
	v_mfma_f32_16x16x32_bf16 v[28:31], v[44:47], v[40:43], v[28:31]
	v_add_f32_e32 v46, v19, v52
	v_or_b32_e32 v68, s23, v146
	v_mfma_f32_16x16x32_bf16 v[20:23], v[36:39], v[40:43], v[20:23]
	ds_read_b64 v[36:37], v136 offset:46848
	ds_read_b64 v[38:39], v137 offset:46848
	v_mov_b64_e32 v[44:45], s[18:19]
	v_mad_i64_i32 v[52:53], s[20:21], v68, s33, v[44:45]
	s_waitcnt lgkmcnt(2)
	v_mov_b32_e32 v47, v46
	v_mov_b32_e32 v250, v46
	s_nop 1
	v_permlane16_swap_b32_e32 v47, v250
	v_add_f32_e32 v55, v47, v250
	s_waitcnt lgkmcnt(0)
	v_mfma_f32_16x16x32_bf16 v[24:27], v[36:39], v[40:43], v[24:27]
	ds_read_b64 v[36:37], v138 offset:27648
	ds_read_b64 v[38:39], v139 offset:27648
	ds_read_b64 v[44:45], v140 offset:34048
	ds_read_b64 v[46:47], v141 offset:34048
	v_sub_f32_e32 v18, v95, v18
	v_mfma_f32_16x16x32_bf16 v[32:35], v[48:51], v[40:43], v[32:35]
	v_cvt_pk_bf16_f32 v41, v63, v54
	v_cvt_pk_bf16_f32 v40, v58, v62
	v_cvt_pk_bf16_f32 v42, v59, v56
	v_cvt_pk_bf16_f32 v43, v57, v19
	ds_read_b64 v[48:49], v142 offset:40448
	ds_read_b64 v[50:51], v143 offset:40448
	s_waitcnt lgkmcnt(2)
	v_mfma_f32_16x16x32_bf16 v[28:31], v[44:47], v[40:43], v[28:31]
	v_exp_f32_e32 v44, v18
	s_waitcnt lgkmcnt(2)
	v_mov_b32_e32 v54, v55
	v_mov_b32_e32 v250, v55
	s_nop 1
	v_permlane32_swap_b32_e32 v54, v250
	v_add_f32_e32 v45, v54, v250
	v_lshl_add_u64 v[18:19], s[8:9], 1, v[52:53]
	v_mfma_f32_16x16x32_bf16 v[20:23], v[36:39], v[40:43], v[20:23]
	ds_read_b64 v[36:37], v144 offset:46848
	ds_read_b64 v[38:39], v145 offset:46848
	v_add_f32_e32 v44, v44, v45
	v_rcp_f32_e32 v44, v44
	v_lshl_add_u64 v[18:19], v[18:19], 0, v[0:1]
	s_waitcnt lgkmcnt(0)
	v_mfma_f32_16x16x32_bf16 v[24:27], v[36:39], v[40:43], v[24:27]
	v_lshl_add_u64 v[36:37], v[18:19], 0, s[28:29]
	v_mul_f32_e32 v20, v44, v20
	v_mul_f32_e32 v21, v44, v21
	v_add_co_u32_e32 v18, vcc, s36, v18
	v_mfma_f32_16x16x32_bf16 v[32:35], v[48:51], v[40:43], v[32:35]
	v_cvt_pk_bf16_f32 v20, v20, v21
	v_mul_f32_e32 v21, v44, v22
	v_addc_co_u32_e32 v19, vcc, 0, v19, vcc
	v_mul_f32_e32 v22, v44, v23
	v_cvt_pk_bf16_f32 v21, v21, v22
	global_store_dwordx2 v[18:19], v[20:21], off offset:2048
	v_mul_f32_e32 v18, v44, v28
	v_mul_f32_e32 v19, v44, v29
	v_cvt_pk_bf16_f32 v18, v18, v19
	v_mul_f32_e32 v19, v44, v30
	v_mul_f32_e32 v20, v44, v31
	v_cvt_pk_bf16_f32 v19, v19, v20
	global_store_dwordx2 v[36:37], v[18:19], off offset:32
	v_mul_f32_e32 v18, v44, v32
	v_mul_f32_e32 v19, v44, v33
	v_cvt_pk_bf16_f32 v18, v18, v19
	v_mul_f32_e32 v19, v44, v34
	v_mul_f32_e32 v20, v44, v35
	v_cvt_pk_bf16_f32 v19, v19, v20
	global_store_dwordx2 v[36:37], v[18:19], off offset:64
	v_mul_f32_e32 v18, v44, v24
	v_mul_f32_e32 v19, v44, v25
	v_cvt_pk_bf16_f32 v18, v18, v19
	v_mul_f32_e32 v19, v44, v26
	s_andn2_b64 vcc, exec, s[16:17]
	s_mov_b64 s[16:17], 0
	v_mul_f32_e32 v20, v44, v27
	v_cvt_pk_bf16_f32 v19, v19, v20
	global_store_dwordx2 v[36:37], v[18:19], off offset:96
	s_cbranch_vccz .LBB0_481
; #define LAS __attribute__((address_space(3)))
; __device__ __forceinline__ unsigned pk2(float lo, float hi) { unsigned r; asm("v_cvt_pk_bf16_f32 %0, %1, %2" : "=v"(r) : "v"(lo), "v"(hi)); return r; }
; __device__ __forceinline__ float bflo(unsigned w) { return __uint_as_float(w << 16); }
; __device__ __forceinline__ float bfhi(unsigned w) { return __uint_as_float(w & 0xffff0000u); }
; __device__ __forceinline__ f32x4 mfma16(bf16x8 a, bf16x8 b, f32x4 c) { return __builtin_amdgcn_mfma_f32_16x16x32_bf16(a, b, c, 0, 0, 0); }
; __device__ __forceinline__ void attn_item(const Args& a, LAS unsigned char* lds, int layer, bool is_sample, int b, int c, int kvh, int seq_row0, int nchunks, bf16_t* proj, const int tid) {
;     ...
;         {
;             float qv[2][8]; float ss = 0.f;
; #pragma unroll
;             for (int ks = 0; ks < 2; ++ks) { const u32x4 w = sub ? qraw[1][ks] : qraw[0][ks];
;                 qv[ks][0] = bflo(w.x); qv[ks][1] = bfhi(w.x); qv[ks][2] = bflo(w.y); qv[ks][3] = bfhi(w.y); qv[ks][4] = bflo(w.z); qv[ks][5] = bfhi(w.z); qv[ks][6] = bflo(w.w); qv[ks][7] = bfhi(w.w);
; #pragma unroll
;                 for (int e = 0; e < 8; ++e) ss += qv[ks][e] * qv[ks][e]; }
;             ss += __shfl_xor(ss, 16); ss += __shfl_xor(ss, 32);
;             const float rs = rsqrtf(ss * (1.f / 64.f) + EPS) * (0.125f * 1.4426950408889634f);
; #pragma unroll
;             for (int ks = 0; ks < 2; ++ks) { const f32x4 g0 = *(const f32x4*)(qng + 32 * ks + 8 * fq), g1 = *(const f32x4*)(qng + 32 * ks + 8 * fq + 4);
;                 u32x4 w; w.x = pk2(qv[ks][0] * rs * g0[0], qv[ks][1] * rs * g0[1]); w.y = pk2(qv[ks][2] * rs * g0[2], qv[ks][3] * rs * g0[3]);
;                 w.z = pk2(qv[ks][4] * rs * g1[0], qv[ks][5] * rs * g1[1]); w.w = pk2(qv[ks][6] * rs * g1[2], qv[ks][7] * rs * g1[3]);
;                 qf[ks] = __builtin_bit_cast(bf16x8, w); }
;         }
;         f32x4 sacc[12];
; #pragma unroll
;         for (int kb = 0; kb < 12; ++kb) { sacc[kb] = (f32x4){0.f, 0.f, 0.f, 0.f};
; #pragma unroll
;             for (int ks = 0; ks < 2; ++ks) { const bf16x8 av = *(const LAS bf16x8*)(lds + L_KS + (16 * kb + fr) * PK + (32 * ks + 8 * fq) * 2); sacc[kb] = mfma16(av, qf[ks], sacc[kb]); } }
.LBB0_477:
	v_cndmask_b32_e64 v21, v10, v2, s[16:17]
	v_cndmask_b32_e64 v20, v11, v3, s[16:17]
	v_and_b32_e32 v31, 0xffff0000, v21
	v_lshlrev_b32_e32 v30, 16, v21
	v_lshlrev_b32_e32 v32, 16, v20
	v_and_b32_e32 v33, 0xffff0000, v20
	v_mul_f32_e32 v20, v31, v31
	v_fmac_f32_e32 v20, v30, v30
	v_cndmask_b32_e64 v19, v12, v4, s[16:17]
	v_fmac_f32_e32 v20, v32, v32
	v_lshlrev_b32_e32 v39, 16, v19
	v_fmac_f32_e32 v20, v33, v33
	v_cndmask_b32_e64 v18, v13, v5, s[16:17]
	v_and_b32_e32 v40, 0xffff0000, v19
	v_fmac_f32_e32 v20, v39, v39
	v_lshlrev_b32_e32 v41, 16, v18
	v_and_b32_e32 v42, 0xffff0000, v18
	v_fmac_f32_e32 v20, v40, v40
	v_cndmask_b32_e64 v18, v14, v6, s[16:17]
	v_fmac_f32_e32 v20, v41, v41
	v_and_b32_e32 v34, 0xffff0000, v18
	v_lshlrev_b32_e32 v35, 16, v18
	v_fmac_f32_e32 v20, v42, v42
	v_cndmask_b32_e64 v23, v15, v7, s[16:17]
	v_pk_mul_f32 v[18:19], v[34:35], v[34:35]
	v_and_b32_e32 v36, 0xffff0000, v23
	v_add_f32_e32 v19, v19, v20
	v_lshlrev_b32_e32 v37, 16, v23
	v_cndmask_b32_e64 v22, v16, v8, s[16:17]
	v_add_f32_e32 v20, v18, v19
	v_pk_mul_f32 v[18:19], v[36:37], v[36:37]
	v_and_b32_e32 v28, 0xffff0000, v22
	v_add_f32_e32 v19, v19, v20
	v_lshlrev_b32_e32 v29, 16, v22
	v_cndmask_b32_e64 v21, v17, v9, s[16:17]
	v_add_f32_e32 v20, v18, v19
	v_pk_mul_f32 v[18:19], v[28:29], v[28:29]
	v_and_b32_e32 v26, 0xffff0000, v21
	v_add_f32_e32 v19, v19, v20
	v_lshlrev_b32_e32 v27, 16, v21
	v_add_f32_e32 v20, v18, v19
	v_pk_mul_f32 v[18:19], v[26:27], v[26:27]
	v_or_b32_e32 v146, s10, v92
	v_add_f32_e32 v19, v19, v20
	v_add_f32_e32 v18, v18, v19
	s_mov_b32 s10, 0x800000
	s_mov_b64 s[20:21], -1
	s_waitcnt lgkmcnt(0)
	v_mov_b32_e32 v19, v18
	v_mov_b32_e32 v250, v18
	s_nop 1
	v_permlane16_swap_b32_e32 v19, v250
	v_add_f32_e32 v18, v19, v250
	s_waitcnt lgkmcnt(0)
	v_mov_b32_e32 v19, v18
	v_mov_b32_e32 v250, v18
	s_nop 1
	v_permlane32_swap_b32_e32 v19, v250
	v_add_f32_e32 v18, v19, v250
	v_fmamk_f32 v18, v18, 0x3c800000, v167
	v_cmp_gt_f32_e32 vcc, s10, v18
	v_mul_f32_e32 v19, 0x4b800000, v18
	s_nop 0
	v_cndmask_b32_e32 v18, v18, v19, vcc
	v_rsq_f32_e32 v18, v18
	s_nop 0
	v_mul_f32_e32 v19, 0x45800000, v18
	v_cndmask_b32_e32 v18, v18, v19, vcc
	v_mul_f32_e32 v38, 0x3e38aa3b, v18
	global_load_dwordx4 v[18:21], v[66:67], off offset:16
	global_load_dwordx4 v[22:25], v[66:67], off
	v_mul_f32_e32 v30, v38, v30
	v_mul_f32_e32 v35, v38, v35
	v_mul_f32_e32 v34, v38, v34
	s_andn2_b64 vcc, exec, s[14:15]
	s_waitcnt vmcnt(0)
	v_mul_f32_e32 v22, v22, v30
	v_mul_f32_e32 v30, v38, v31
	v_mul_f32_e32 v23, v23, v30
	v_cvt_pk_bf16_f32 v30, v22, v23
	v_mul_f32_e32 v22, v38, v32
	v_mul_f32_e32 v22, v24, v22
	v_mul_f32_e32 v23, v38, v33
	v_mul_f32_e32 v23, v25, v23
	v_cvt_pk_bf16_f32 v31, v22, v23
	v_mul_f32_e32 v22, v38, v39
	v_mul_f32_e32 v18, v18, v22
	v_mul_f32_e32 v22, v38, v40
	v_mul_f32_e32 v19, v19, v22
	v_cvt_pk_bf16_f32 v32, v18, v19
	v_mul_f32_e32 v18, v38, v41
	v_mul_f32_e32 v19, v38, v42
	v_mul_f32_e32 v18, v20, v18
	v_mul_f32_e32 v19, v21, v19
	v_cvt_pk_bf16_f32 v33, v18, v19
	global_load_dwordx4 v[18:21], v[66:67], off offset:144
	global_load_dwordx4 v[22:25], v[66:67], off offset:128
	ds_read_b128 v[74:77], v97 offset:23104
	s_waitcnt vmcnt(0)
	v_mul_f32_e32 v22, v22, v35
	v_mul_f32_e32 v23, v23, v34
	v_cvt_pk_bf16_f32 v34, v22, v23
	v_mul_f32_e32 v22, v38, v37
	v_mul_f32_e32 v22, v24, v22
	v_mul_f32_e32 v23, v38, v36
	v_mul_f32_e32 v23, v25, v23
	v_cvt_pk_bf16_f32 v35, v22, v23
	v_mul_f32_e32 v22, v38, v29
	v_mul_f32_e32 v18, v18, v22
	v_mul_f32_e32 v22, v38, v28
	v_mul_f32_e32 v19, v19, v22
	v_cvt_pk_bf16_f32 v36, v18, v19
	v_mul_f32_e32 v18, v38, v27
	v_mul_f32_e32 v19, v38, v26
	v_mul_f32_e32 v18, v20, v18
	v_mul_f32_e32 v19, v21, v19
	v_cvt_pk_bf16_f32 v37, v18, v19
	ds_read_b128 v[18:21], v97
	ds_read_b128 v[22:25], v97 offset:64
	s_waitcnt lgkmcnt(1)
	v_mfma_f32_16x16x32_bf16 v[18:21], v[18:21], v[30:33], 0
	ds_read_b128 v[26:29], v97 offset:20800
	s_waitcnt lgkmcnt(1)
	v_mfma_f32_16x16x32_bf16 v[62:65], v[22:25], v[34:37], v[18:21]
	ds_read_b128 v[22:25], v97 offset:2368
	s_nop 3
	ds_read_b128 v[18:21], v97 offset:2304
	s_waitcnt lgkmcnt(0)
	v_mfma_f32_16x16x32_bf16 v[18:21], v[18:21], v[30:33], 0
	v_mfma_f32_16x16x32_bf16 v[70:73], v[22:25], v[34:37], v[18:21]
	ds_read_b128 v[22:25], v97 offset:4672
	s_nop 5
	ds_read_b128 v[18:21], v97 offset:4608
	s_waitcnt lgkmcnt(0)
	v_mfma_f32_16x16x32_bf16 v[18:21], v[18:21], v[30:33], 0
	v_mfma_f32_16x16x32_bf16 v[38:41], v[22:25], v[34:37], v[18:21]
	ds_read_b128 v[22:25], v97 offset:6976
	s_nop 5
	ds_read_b128 v[18:21], v97 offset:6912
	s_waitcnt lgkmcnt(0)
	v_mfma_f32_16x16x32_bf16 v[18:21], v[18:21], v[30:33], 0
	v_mfma_f32_16x16x32_bf16 v[58:61], v[22:25], v[34:37], v[18:21]
	ds_read_b128 v[22:25], v97 offset:9280
	s_nop 5
	ds_read_b128 v[18:21], v97 offset:9216
	s_waitcnt lgkmcnt(0)
	v_mfma_f32_16x16x32_bf16 v[18:21], v[18:21], v[30:33], 0
	v_mfma_f32_16x16x32_bf16 v[42:45], v[22:25], v[34:37], v[18:21]
	ds_read_b128 v[22:25], v97 offset:11584
	s_nop 5
	ds_read_b128 v[18:21], v97 offset:11520
	s_waitcnt lgkmcnt(0)
; #define LAS __attribute__((address_space(3)))
; __device__ __forceinline__ f32x4 mfma16(bf16x8 a, bf16x8 b, f32x4 c) { return __builtin_amdgcn_mfma_f32_16x16x32_bf16(a, b, c, 0, 0, 0); }
; __device__ __forceinline__ void attn_item(const Args& a, LAS unsigned char* lds, int layer, bool is_sample, int b, int c, int kvh, int seq_row0, int nchunks, bf16_t* proj, const int tid) {
;     ...
;         for (int kb = 0; kb < 12; ++kb) { sacc[kb] = (f32x4){0.f, 0.f, 0.f, 0.f};
; #pragma unroll
;             for (int ks = 0; ks < 2; ++ks) { const bf16x8 av = *(const LAS bf16x8*)(lds + L_KS + (16 * kb + fr) * PK + (32 * ks + 8 * fq) * 2); sacc[kb] = mfma16(av, qf[ks], sacc[kb]); } }
;         float mx = sink;
; #pragma unroll
;         for (int kb = 0; kb < 12; ++kb)
; #pragma unroll
;             for (int j = 0; j < 4; ++j) { const int kl = 16 * kb + 4 * fq + j;
;                 const float s = sacc[kb][j] + bt[g * 256 + kl - 128 - ql + 191];
;                 sacc[kb][j] = s; mx = fmaxf(mx, s); }
;         if (kmin > 0) {
;             mx = sink;
; #pragma unroll
;             for (int kb = 0; kb < 12; ++kb)
; #pragma unroll
;                 for (int j = 0; j < 4; ++j) { const int kl = 16 * kb + 4 * fq + j; if (kl < kmin) sacc[kb][j] = -INFINITY; mx = fmaxf(mx, sacc[kb][j]); }
;         }
;         mx = fmaxf(mx, __shfl_xor(mx, 16)); mx = fmaxf(mx, __shfl_xor(mx, 32));
	v_mfma_f32_16x16x32_bf16 v[18:21], v[18:21], v[30:33], 0
	v_mfma_f32_16x16x32_bf16 v[54:57], v[22:25], v[34:37], v[18:21]
	ds_read_b128 v[22:25], v97 offset:13888
	s_nop 5
	ds_read_b128 v[18:21], v97 offset:13824
	s_waitcnt lgkmcnt(0)
	v_mfma_f32_16x16x32_bf16 v[18:21], v[18:21], v[30:33], 0
	v_mfma_f32_16x16x32_bf16 v[46:49], v[22:25], v[34:37], v[18:21]
	ds_read_b128 v[22:25], v97 offset:16192
	s_nop 5
	ds_read_b128 v[18:21], v97 offset:16128
	s_waitcnt lgkmcnt(0)
	v_mfma_f32_16x16x32_bf16 v[18:21], v[18:21], v[30:33], 0
	v_mfma_f32_16x16x32_bf16 v[50:53], v[22:25], v[34:37], v[18:21]
	ds_read_b128 v[22:25], v97 offset:18496
	s_nop 5
	ds_read_b128 v[18:21], v97 offset:18432
	s_waitcnt lgkmcnt(0)
	v_mfma_f32_16x16x32_bf16 v[18:21], v[18:21], v[30:33], 0
	v_mfma_f32_16x16x32_bf16 v[18:21], v[22:25], v[34:37], v[18:21]
	ds_read_b128 v[22:25], v97 offset:20736
	s_waitcnt lgkmcnt(0)
	v_mfma_f32_16x16x32_bf16 v[22:25], v[22:25], v[30:33], 0
	v_mfma_f32_16x16x32_bf16 v[22:25], v[26:29], v[34:37], v[22:25]
	ds_read_b128 v[26:29], v97 offset:23040
	s_waitcnt lgkmcnt(0)
	v_mfma_f32_16x16x32_bf16 v[26:29], v[26:29], v[30:33], 0
	v_mfma_f32_16x16x32_bf16 v[26:29], v[74:77], v[34:37], v[26:29]
	ds_read_b128 v[74:77], v97 offset:25344
	s_waitcnt lgkmcnt(0)
	v_mfma_f32_16x16x32_bf16 v[30:33], v[74:77], v[30:33], 0
	ds_read_b128 v[74:77], v97 offset:25408
	s_waitcnt lgkmcnt(0)
	v_mfma_f32_16x16x32_bf16 v[32:35], v[74:77], v[34:37], v[30:33]
	s_nop 4
	v_sub_u32_e32 v30, v96, v146
	v_lshl_add_u32 v90, v30, 2, 0
	v_add_u32_e32 v30, 0xd0fc, v90
	ds_read2_b32 v[30:31], v30 offset1:1
	v_add_u32_e32 v36, 0xd13c, v90
	ds_read2_b32 v[36:37], v36 offset1:1
	v_add_u32_e32 v78, 0xd304, v90
	ds_read2_b32 v[78:79], v78 offset1:1
	s_waitcnt lgkmcnt(2)
	v_pk_add_f32 v[68:69], v[62:63], v[30:31]
	v_add_u32_e32 v30, 0xd104, v90
	ds_read2_b32 v[30:31], v30 offset1:1
	s_waitcnt lgkmcnt(2)
	v_pk_add_f32 v[62:63], v[70:71], v[36:37]
	v_add_u32_e32 v36, 0xd144, v90
	ds_read2_b32 v[70:71], v36 offset1:1
	v_add_u32_e32 v80, 0xd33c, v90
	ds_read2_b32 v[80:81], v80 offset1:1
	s_waitcnt lgkmcnt(2)
	v_add_f32_e32 v30, v64, v30
	v_add_u32_e32 v64, 0xd17c, v90
	s_waitcnt lgkmcnt(1)
	v_add_f32_e32 v36, v72, v70
	v_mov_b32_e32 v72, v65
	ds_read2_b32 v[64:65], v64 offset1:1
	v_add_u32_e32 v82, 0xd344, v90
	v_mov_b32_e32 v70, v31
	ds_read2_b32 v[82:83], v82 offset1:1
	v_pk_add_f32 v[70:71], v[72:73], v[70:71]
	s_waitcnt lgkmcnt(1)
	v_pk_add_f32 v[64:65], v[38:39], v[64:65]
	v_add_u32_e32 v38, 0xd184, v90
	ds_read2_b32 v[38:39], v38 offset1:1
	v_add_u32_e32 v84, 0xd37c, v90
	ds_read2_b32 v[84:85], v84 offset1:1
	v_add_u32_e32 v86, 0xd384, v90
	ds_read2_b32 v[86:87], v86 offset1:1
	s_waitcnt lgkmcnt(2)
	v_add_f32_e32 v38, v40, v38
	v_add_u32_e32 v40, 0xd1bc, v90
	ds_read2_b32 v[72:73], v40 offset1:1
	v_add_u32_e32 v40, 0xd1c4, v90
	v_add_u32_e32 v88, 0xd3bc, v90
	ds_read2_b32 v[88:89], v88 offset1:1
	v_mov_b32_e32 v37, v70
	s_waitcnt lgkmcnt(1)
	v_pk_add_f32 v[58:59], v[58:59], v[72:73]
	ds_read2_b32 v[72:73], v40 offset1:1
	v_mov_b32_e32 v31, v71
	s_waitcnt lgkmcnt(0)
	v_add_f32_e32 v40, v60, v72
	v_mov_b32_e32 v60, v41
	v_mov_b32_e32 v72, v39
	v_pk_add_f32 v[72:73], v[60:61], v[72:73]
	v_add_u32_e32 v60, 0xd1fc, v90
	ds_read2_b32 v[60:61], v60 offset1:1
	v_mov_b32_e32 v41, v72
	v_mov_b32_e32 v39, v73
	s_waitcnt lgkmcnt(0)
	v_pk_add_f32 v[60:61], v[42:43], v[60:61]
	v_add_u32_e32 v42, 0xd204, v90
	ds_read2_b32 v[42:43], v42 offset1:1
	s_waitcnt lgkmcnt(0)
	v_add_f32_e32 v42, v44, v42
	v_add_u32_e32 v44, 0xd23c, v90
	ds_read2_b32 v[74:75], v44 offset1:1
	v_add_u32_e32 v44, 0xd244, v90
	s_waitcnt lgkmcnt(0)
	v_pk_add_f32 v[54:55], v[54:55], v[74:75]
	ds_read2_b32 v[74:75], v44 offset1:1
	s_waitcnt lgkmcnt(0)
	v_add_f32_e32 v44, v56, v74
	v_mov_b32_e32 v56, v45
	v_mov_b32_e32 v74, v43
	v_pk_add_f32 v[74:75], v[56:57], v[74:75]
	v_add_u32_e32 v56, 0xd27c, v90
	ds_read2_b32 v[56:57], v56 offset1:1
	v_mov_b32_e32 v45, v74
	v_mov_b32_e32 v43, v75
	s_waitcnt lgkmcnt(0)
	v_pk_add_f32 v[56:57], v[46:47], v[56:57]
	v_add_u32_e32 v46, 0xd284, v90
	ds_read2_b32 v[46:47], v46 offset1:1
	s_waitcnt lgkmcnt(0)
	v_add_f32_e32 v46, v48, v46
	v_add_u32_e32 v48, 0xd2bc, v90
	ds_read2_b32 v[76:77], v48 offset1:1
	v_add_u32_e32 v48, 0xd2c4, v90
	s_waitcnt lgkmcnt(0)
	v_pk_add_f32 v[50:51], v[50:51], v[76:77]
	ds_read2_b32 v[76:77], v48 offset1:1
	s_waitcnt lgkmcnt(0)
	v_add_f32_e32 v48, v52, v76
	v_mov_b32_e32 v52, v49
	v_mov_b32_e32 v76, v47
	v_pk_add_f32 v[52:53], v[52:53], v[76:77]
	v_add_u32_e32 v76, 0xd2fc, v90
	v_add_u32_e32 v90, 0xd3c4, v90
	ds_read2_b32 v[76:77], v76 offset1:1
	ds_read2_b32 v[90:91], v90 offset1:1
	v_mov_b32_e32 v49, v52
	v_mov_b32_e32 v47, v53
	s_cbranch_vccnz .LBB0_479
	v_max3_f32 v147, v95, v68, v69
	v_max3_f32 v147, v147, v30, v70
	v_max3_f32 v147, v147, v62, v63
	v_max3_f32 v147, v147, v36, v71
	v_max3_f32 v147, v147, v64, v65
	v_max3_f32 v147, v147, v38, v72
	v_max3_f32 v147, v147, v58, v59
	v_max3_f32 v147, v147, v40, v73
	v_max3_f32 v147, v147, v60, v61
	v_max3_f32 v147, v147, v42, v74
	v_max3_f32 v147, v147, v54, v55
	v_max3_f32 v147, v147, v44, v75
	v_max3_f32 v147, v147, v56, v57
	v_max3_f32 v147, v147, v46, v52
	v_max3_f32 v147, v147, v50, v51
	v_max3_f32 v147, v147, v48, v53
	s_mov_b64 s[20:21], 0
